# v18: RWKV scans: w2T/a2T LDS matrices get the same XOR swizzle as the other [64][72] bf16 matrices (8 conflict-free fragment reads per chunk)
# speedup vs baseline: 1.0147x; 1.0062x over previous
; __device__ __forceinline__ unsigned f2bf(float f) { return pk2(f, 0.f) & 0xffffu; }
; template <bool PA> ...
;     bf16* M = (bf16*)lds;
;     ...
;     bf16* w2T = MAT(13); bf16* a2T = MAT(14); float* wc = (float*)MAT(15); float* cst = wc + 64;
;     float* zbuf = (float*)MAT(0); float* abuf = zbuf + 4096;
;     float* cumb = (float*)MAT(10); float* segtot = cumb + 4096;
;     const int nch = slab == 0 ? 129 : 257, G = slab == 0 ? 4 : 8, nitems = 256, NCHA = nch;
;     const int lane = tid & 63, wave = tid >> 6, r16 = lane & 15, kq = lane >> 4, mt = wave >> 1, ntb = 2 * (wave & 1);
;     const int j = tid >> 3, part = tid & 7, c8 = part * 8;
;     const int tunit = ((j >> 3) + 1) * (4 * (j >> 3) + (j & 7)) + part; const bool tlow = part <= (j >> 3);
;     for (int item = blockIdx.x; item < nitems; item += gridDim.x) {
;         const int g = item % G, strm = item / G; const int p0 = g == 0 ? 0 : 1 + 32 * g, p1 = 33 + 32 * g;
;         const bool haveT = !PA;
;         const int d = strm & 1, head = (strm >> 1) & 15, sq = strm >> 5; const int seqbase = sq * 8256; const int hc8 = head * 64 + c8;
;         bf16* Op = d ? OBb : OFb;
;         const float* w0 = a->in[15] + d * 1024; const float* w2 = a->in[17] + (size_t)d * 64 * 1024; const float* a0 = a->in[18] + d * 1024; const float* a2 = a->in[20] + (size_t)d * 64 * 1024;
;         __syncthreads();
;         if (tid < 320) { const int wch = tid >> 6, cc = tid & 63; const float* src = wch == 0 ? w0 : (wch == 1 ? a0 : (wch == 2 ? a->in[23] : (wch == 3 ? a->in[24] : a->in[25]))); cst[tid] = src[head * 64 + cc]; }
;         for (int i = tid; i < 4096; i += 512) { const int l = i >> 6, cc = i & 63; w2T[cc * 72 + l] = (bf16)f2bf(w2[(size_t)l * 1024 + head * 64 + cc]); a2T[cc * 72 + l] = (bf16)f2bf(a2[(size_t)l * 1024 + head * 64 + cc]); }
;         f32x4_t Sacc[2], S2acc[2]; Sacc[0] = (f32x4_t){0.f, 0.f, 0.f, 0.f}; Sacc[1] = Sacc[0];
; #pragma unroll
;         for (int i = 0; i < 2; ++i)
; #pragma unroll
;             for (int e = 0; e < 4; ++e) S2acc[i][e] = (16 * mt + 4 * kq + e == 16 * (ntb + i) + r16) ? 1.f : 0.f;
;         __syncthreads();
.LBB0_123:
	s_and_b64 vcc, exec, s[0:1]
	s_cbranch_vccz .LBB0_388
	s_cmp_lt_i32 s65, 9
	s_mov_b64 s[0:1], -1
	s_cbranch_scc1 .LBB0_251
	s_cmp_gt_i32 s65, 9
	s_cbranch_scc0 .LBB0_190
	v_readlane_b32 s0, v253, 2
	v_writelane_b32 v255, s70, 18
	v_readlane_b32 s1, v253, 3
	s_mov_b32 s39, s40
	v_writelane_b32 v255, s71, 19
	s_andn2_b64 vcc, exec, s[0:1]
	s_cbranch_vccnz .LBB0_189
	s_add_u32 s0, s6, 0x9a00000
	s_addc_u32 s1, s7, 0
	v_writelane_b32 v255, s0, 30
	v_ashrrev_i32_e32 v83, 6, v202
	v_ashrrev_i32_e32 v84, 3, v202
	v_writelane_b32 v255, s1, 31
	s_add_u32 s0, s6, 0xba80000
	s_addc_u32 s1, s7, 0
	v_writelane_b32 v255, s0, 34
	v_lshlrev_b32_e32 v0, 1, v83
	v_and_b32_e32 v9, 2, v0
	v_writelane_b32 v255, s1, 35
	s_add_u32 s0, s6, 0xdb00000
	s_addc_u32 s1, s7, 0
	v_writelane_b32 v255, s0, 28
	v_and_b32_e32 v0, 7, v84
	v_lshl_add_u32 v0, v83, 2, v0
	v_writelane_b32 v255, s1, 29
	s_add_u32 s0, s6, 0x100000
	v_writelane_b32 v255, s0, 14
	s_addc_u32 s0, s7, 0
	v_writelane_b32 v255, s0, 15
	s_cmp_eq_u32 s39, 0
	s_movk_i32 s0, 0x81
	s_cselect_b32 s91, s0, 0x101
	v_mad_u64_u32 v[2:3], s[0:1], v0, v83, v[0:1]
	v_readlane_b32 s0, v255, 5
	v_readlane_b32 s1, v255, 6
	s_load_dwordx2 s[10:11], s[0:1], 0x78
	s_load_dwordx4 s[20:23], s[0:1], 0x88
	s_load_dwordx2 s[42:43], s[0:1], 0xa0
	s_movk_i32 s0, 0x140
	v_cmp_gt_i32_e64 s[0:1], s0, v202
	s_waitcnt lgkmcnt(0)
	v_writelane_b32 v255, s10, 10
	v_and_b32_e32 v10, 15, v203
	v_bfe_u32 v11, v203, 4, 2
	v_writelane_b32 v255, s11, 11
	v_writelane_b32 v255, s20, 22
	v_and_b32_e32 v13, -16, v84
	v_lshl_or_b32 v14, v11, 2, v13
	v_writelane_b32 v255, s21, 23
	v_writelane_b32 v255, s22, 24
	v_writelane_b32 v255, s23, 25
	v_writelane_b32 v255, s0, 32
	v_lshlrev_b32_e32 v3, 1, v10
	v_add_u32_e32 v0, 0, v3
	v_writelane_b32 v255, s1, 33
	v_cmp_lt_u32_e64 s[0:1], 63, v202
	v_lshlrev_b32_e32 v17, 5, v9
	v_lshl_or_b32 v22, v9, 4, v10
	v_writelane_b32 v255, s0, 12
	v_and_b32_e32 v8, 7, v203
	v_and_b32_e32 v20, 48, v203
	v_writelane_b32 v255, s1, 13
	s_movk_i32 s0, 0x1000
	v_cmp_gt_i32_e64 s[10:11], s0, v202
	s_cselect_b32 s0, 2, 3
	v_and_b32_e32 v82, 63, v203
	v_writelane_b32 v255, s10, 20
	s_mov_b64 s[12:13], 0x730000
	v_lshlrev_b32_e32 v12, 2, v202
	v_writelane_b32 v255, s11, 21
	v_writelane_b32 v255, s0, 26
	s_movk_i32 s0, 0x90
	v_mul_lo_u32 v16, v14, s0
	v_add3_u32 v87, v0, v16, v17
	v_bfi_b32 v0, -16, v84, v203
	v_mul_lo_u32 v18, v0, s0
	v_mul_u32_u24_e32 v0, 0x48, v22
	v_lshlrev_b32_e32 v23, 1, v0
	v_lshlrev_b32_e32 v0, 4, v8
	s_waitcnt vmcnt(0)
	v_mul_lo_u32 v30, v84, s0
	v_readlane_b32 s0, v254, 31
	v_lshl_add_u64 v[6:7], s[6:7], 0, v[0:1]
	v_lshlrev_b32_e32 v25, 2, v82
	v_add3_u32 v93, s0, v20, v23
	v_readlane_b32 s0, v254, 32
	v_lshl_add_u64 v[42:43], v[6:7], 0, s[12:13]
	s_mov_b64 s[12:13], 0xb40000
	v_add3_u32 v94, s0, v20, v23
	v_readlane_b32 s0, v254, 33
	v_add_u32_e32 v24, 0, v0
	v_lshl_add_u64 v[44:45], v[6:7], 0, s[12:13]
	v_lshlrev_b32_e32 v6, 8, v84
	v_add_u32_e32 v98, s0, v12
	v_add_u32_e32 v99, s0, v25
	v_readlane_b32 s0, v254, 28
	v_add_u32_e32 v21, 0, v20
	v_readlane_b32 s2, v254, 27
	v_add3_u32 v95, v24, v0, v6
	v_lshlrev_b32_e32 v7, 5, v8
	v_add3_u32 v101, s0, v0, v30
	v_add_u32_e32 v0, 0x900, v23
	v_add3_u32 v97, s2, v7, v6
	v_add_u32_e32 v6, v21, v0
	v_readlane_b32 s1, v254, 26
	v_lshlrev_b32_e32 v19, 3, v11
	v_add_u32_e32 v105, 0xfc00, v6
	v_add_u32_e32 v106, 0xfc40, v6
	v_lshlrev_b32_e32 v6, 1, v13
	s_cselect_b32 s8, 4, 8
	v_add_u32_e32 v86, s1, v12
	v_add_u32_e32 v26, s2, v25
	v_add_u32_e32 v27, s2, v3
	v_readlane_b32 s9, v254, 29
	v_readlane_b32 s10, v254, 30
	v_add3_u32 v107, s2, v18, v20
	v_add3_u32 v12, 0, v6, v19
	s_mov_b32 s2, 0xfc00
	v_add3_u32 v110, s0, v18, v20
	s_add_i32 s0, 0, 0x12000
	v_add_u32_e32 v28, s9, v3
	v_add_u32_e32 v29, s10, v3
	v_add3_u32 v109, v12, v0, s2
	v_add_u32_e32 v0, s0, v6
	v_lshlrev_b32_e32 v85, 3, v8
	v_cmp_le_i32_e64 s[36:37], v8, v83
	v_add_lshl_u32 v2, v2, v8, 3
	v_add_u32_e32 v96, s1, v7
	v_cmp_eq_u32_e64 s[44:45], 0, v8
	v_readlane_b32 s1, v254, 34
	v_add3_u32 v102, v27, v16, v17
	v_add3_u32 v103, v28, v16, v17
	v_add3_u32 v104, v29, v16, v17
	v_add3_u32 v111, v0, v19, v23
	v_add_u32_e32 v0, s0, v20
	v_or_b32_e32 v16, 1, v9
	v_mul_u32_u24_e32 v8, 0x240, v8
	v_lshlrev_b32_e32 v15, 1, v84
	v_add_u32_e32 v113, v0, v23
	v_add_u32_e32 v115, v0, v18
	v_lshl_add_u32 v0, v10, 2, s1
	v_or_b32_e32 v6, 1, v14
	v_lshl_or_b32 v10, v16, 4, v10
	v_lshlrev_b32_e32 v8, 1, v8
	v_add3_u32 v117, 0, v15, v8
	v_add3_u32 v118, 0, v8, v15
	v_lshlrev_b32_e32 v15, 6, v6
	v_cmp_gt_i32_e64 s[78:79], v22, v6
	v_cmp_gt_i32_e64 s[84:85], v10, v6
	v_cvt_f32_ubyte0_e32 v6, s8
	v_rcp_iflag_f32_e32 v6, v6
	v_lshlrev_b32_e32 v4, 6, v84
	v_ashrrev_i32_e32 v5, 31, v4
	v_lshlrev_b64 v[46:47], 2, v[4:5]
	v_mul_f32_e32 v6, 0x4f7ffffe, v6
	v_cvt_u32_f32_e32 v6, v6
	v_and_b32_e32 v4, 0xfffffc00, v4
	v_lshlrev_b32_e32 v5, 8, v11
	v_add_u32_e32 v108, v12, v23
	v_or_b32_e32 v12, 2, v14
	v_or_b32_e32 v13, 3, v14
	v_or3_b32 v4, v4, v5, v22
	v_add_u32_e32 v89, v21, v23
	v_add_u32_e32 v92, v21, v18
	v_add_u32_e32 v100, s1, v7
	v_lshlrev_b32_e32 v17, 6, v14
	v_lshlrev_b32_e32 v19, 6, v12
	v_lshlrev_b32_e32 v21, 6, v13
	v_readfirstlane_b32 s1, v6
	v_or_b32_e32 v6, 64, v4
	v_add3_u32 v88, 0, v18, v20
	v_add3_u32 v112, s9, v18, v20
	v_add3_u32 v114, s10, v18, v20
	v_or_b32_e32 v18, v10, v17
	v_or_b32_e32 v8, v22, v17
	v_or_b32_e32 v17, v15, v22
	v_or_b32_e32 v20, v19, v22
	v_or_b32_e32 v23, v21, v22
	v_or_b32_e32 v15, v10, v15
	v_or_b32_e32 v19, v10, v19
	v_or_b32_e32 v21, v10, v21
	v_cmp_lt_i32_e64 s[70:71], v10, v14
	v_cmp_gt_i32_e64 s[72:73], v10, v14
	v_cmp_lt_i32_e64 s[74:75], v10, v12
; template <bool PA> ...
;     ...
;     bf16* w2T = MAT(13); bf16* a2T = MAT(14); float* wc = (float*)MAT(15); float* cst = wc + 64;
;     float* zbuf = (float*)MAT(0); float* abuf = zbuf + 4096;
;     float* cumb = (float*)MAT(10); float* segtot = cumb + 4096;
;     const int nch = slab == 0 ? 129 : 257, G = slab == 0 ? 4 : 8, nitems = 256, NCHA = nch;
;     const int lane = tid & 63, wave = tid >> 6, r16 = lane & 15, kq = lane >> 4, mt = wave >> 1, ntb = 2 * (wave & 1);
;     const int j = tid >> 3, part = tid & 7, c8 = part * 8;
;     const int tunit = ((j >> 3) + 1) * (4 * (j >> 3) + (j & 7)) + part; const bool tlow = part <= (j >> 3);
	v_cmp_lt_i32_e64 s[76:77], v10, v13
	v_cmp_gt_i32_e64 s[86:87], v10, v12
	v_cmp_gt_i32_e64 s[88:89], v10, v13
	v_or_b32_e32 v46, v46, v7
	v_mov_b64_e32 v[10:11], 0x1800000
	v_ashrrev_i32_e32 v7, 31, v6
	v_lshl_add_u64 v[50:51], v[6:7], 2, v[10:11]
	v_or_b32_e32 v6, 0x80, v4
	v_ashrrev_i32_e32 v7, 31, v6
	v_lshl_add_u64 v[52:53], v[6:7], 2, v[10:11]
	v_or_b32_e32 v6, 0xc0, v4
	v_ashrrev_i32_e32 v7, 31, v6
	v_lshl_add_u64 v[54:55], v[6:7], 2, v[10:11]
	v_or_b32_e32 v6, 16, v4
	s_sub_i32 s0, 0, s8
	v_ashrrev_i32_e32 v7, 31, v6
	s_mul_i32 s0, s0, s1
	v_lshl_add_u64 v[56:57], v[6:7], 2, v[10:11]
	v_or_b32_e32 v6, 0x50, v4
	v_ashrrev_i32_e32 v3, 31, v2
	s_mul_hi_u32 s0, s1, s0
	v_ashrrev_i32_e32 v5, 31, v4
	v_ashrrev_i32_e32 v7, 31, v6
	s_add_i32 s10, s1, s0
	v_lshl_add_u64 v[48:49], v[4:5], 2, v[10:11]
	v_lshl_add_u64 v[58:59], v[6:7], 2, v[10:11]
	v_or_b32_e32 v6, 0x90, v4
	v_or_b32_e32 v4, 0xd0, v4
	v_lshl_add_u64 v[2:3], v[2:3], 1, s[6:7]
	s_mov_b64 s[0:1], 0x2000000
	v_add_u32_e32 v91, v24, v30
	v_lshlrev_b32_e32 v24, 11, v83
	v_lshl_add_u32 v119, v8, 2, 0
	v_lshlrev_b32_e32 v8, 6, v9
	v_lshlrev_b32_e32 v9, 6, v16
	v_ashrrev_i32_e32 v7, 31, v6
	v_ashrrev_i32_e32 v5, 31, v4
	v_lshl_add_u64 v[64:65], v[2:3], 0, s[0:1]
	s_add_i32 s0, s91, -1
	v_sub_u32_e32 v90, 63, v84
	v_cmp_eq_u32_e64 s[46:47], 63, v84
	v_mul_u32_u24_e32 v116, 0x48, v82
	v_lshl_add_u32 v120, v17, 2, 0
	v_lshl_add_u32 v121, v20, 2, 0
	v_lshl_add_u32 v122, v23, 2, 0
	v_lshl_add_u32 v123, v18, 2, 0
	v_lshl_add_u32 v124, v15, 2, 0
	v_lshl_add_u32 v125, v19, 2, 0
	v_lshl_add_u32 v126, v21, 2, 0
	v_cmp_lt_i32_e64 s[48:49], 0, v83
	v_cmp_lt_i32_e64 s[50:51], 1, v83
	v_cmp_lt_i32_e64 s[52:53], 2, v83
	v_cmp_lt_i32_e64 s[54:55], 3, v83
	v_cmp_lt_i32_e64 s[56:57], 4, v83
	v_cmp_lt_i32_e64 s[58:59], 5, v83
	v_cmp_lt_i32_e64 s[60:61], 6, v83
	v_cmp_lt_i32_e64 s[62:63], v22, v14
	v_cmp_gt_i32_e64 s[64:65], v22, v14
	v_cmp_lt_i32_e64 s[66:67], v22, v12
	v_cmp_lt_i32_e64 s[68:69], v22, v13
	v_cmp_gt_i32_e64 s[80:81], v22, v12
	v_cmp_gt_i32_e64 s[82:83], v22, v13
	v_lshl_add_u64 v[60:61], v[6:7], 2, v[10:11]
	v_lshl_add_u64 v[62:63], v[4:5], 2, v[10:11]
	v_writelane_b32 v255, s0, 16
	v_add_u32_e32 v127, v0, v8
	v_add_u32_e32 v128, v0, v9
	v_add_u32_e32 v129, v26, v24
	v_readfirstlane_b32 s9, v202
	v_mov_b32_e32 v176, v117
	s_mov_b32 s0, 0xff0000
	s_mov_b32 s1, 0xff
	v_cndmask_b32_e64 v201, 0, 16, s[0:1]
	s_mov_b32 s0, 0xff000000
	s_mov_b32 s1, 0xff00
	v_cndmask_b32_e64 v252, 0, 16, s[0:1]
	v_sub_u32_e32 v201, v201, v252
	v_add_u32_e32 v87, v87, v201
	s_mov_b32 s0, 0xff0
	s_mov_b32 s1, 0xff0
	v_cndmask_b32_e64 v201, 0, 16, s[0:1]
	s_mov_b32 s0, 0xff00000
	s_mov_b32 s1, 0xff00000
	v_cndmask_b32_e64 v252, 0, 16, s[0:1]
	v_sub_u32_e32 v201, v201, v252
	v_add_u32_e32 v88, v88, v201
	s_mov_b32 s0, 0xff0
	s_mov_b32 s1, 0xff0
	v_cndmask_b32_e64 v201, 0, 16, s[0:1]
	s_mov_b32 s0, 0xff00000
	s_mov_b32 s1, 0xff00000
	v_cndmask_b32_e64 v252, 0, 16, s[0:1]
	v_sub_u32_e32 v201, v201, v252
	v_add_u32_e32 v89, v89, v201
	s_mov_b32 s0, 0x0
	s_mov_b32 s1, 0x55555555
	s_bitcmp1_b32 s9, 6
	s_cmov_b32 s0, 0x55555555
	s_cmov_b32 s1, 0x0
	v_cndmask_b32_e64 v201, 0, 16, s[0:1]
	s_mov_b32 s0, 0x0
	s_mov_b32 s1, 0xaaaaaaaa
	s_bitcmp1_b32 s9, 6
	s_cmov_b32 s0, 0xaaaaaaaa
	s_cmov_b32 s1, 0x0
	v_cndmask_b32_e64 v252, 0, 16, s[0:1]
	v_sub_u32_e32 v201, v201, v252
	v_add_u32_e32 v91, v91, v201
	s_mov_b32 s0, 0xff0
	s_mov_b32 s1, 0xff0
	v_cndmask_b32_e64 v201, 0, 16, s[0:1]
	s_mov_b32 s0, 0xff00000
	s_mov_b32 s1, 0xff00000
	v_cndmask_b32_e64 v252, 0, 16, s[0:1]
	v_sub_u32_e32 v201, v201, v252
	v_add_u32_e32 v92, v92, v201
	s_mov_b32 s0, 0x0
	s_mov_b32 s1, 0x55555555
	s_bitcmp1_b32 s9, 6
	s_cmov_b32 s0, 0x55555555
	s_cmov_b32 s1, 0x0
	v_cndmask_b32_e64 v201, 0, 16, s[0:1]
	s_mov_b32 s0, 0x0
	s_mov_b32 s1, 0xaaaaaaaa
	s_bitcmp1_b32 s9, 6
	s_cmov_b32 s0, 0xaaaaaaaa
	s_cmov_b32 s1, 0x0
	v_cndmask_b32_e64 v252, 0, 16, s[0:1]
	v_sub_u32_e32 v201, v201, v252
	v_add_u32_e32 v101, v101, v201
	s_mov_b32 s0, 0xff0000
	s_mov_b32 s1, 0xff
	v_cndmask_b32_e64 v201, 0, 16, s[0:1]
	s_mov_b32 s0, 0xff000000
	s_mov_b32 s1, 0xff00
	v_cndmask_b32_e64 v252, 0, 16, s[0:1]
	v_sub_u32_e32 v201, v201, v252
	v_add_u32_e32 v102, v102, v201
	s_mov_b32 s0, 0xff0000
	s_mov_b32 s1, 0xff
	v_cndmask_b32_e64 v201, 0, 16, s[0:1]
	s_mov_b32 s0, 0xff000000
	s_mov_b32 s1, 0xff00
	v_cndmask_b32_e64 v252, 0, 16, s[0:1]
	v_sub_u32_e32 v201, v201, v252
	v_add_u32_e32 v103, v103, v201
; __device__ __forceinline__ void mm2(f32x4_t (&acc)[2], const bf16* A, const bf16* Bt, int mt, int ntb, int r16, int kq) {
; #pragma unroll
;     for (int kk = 0; kk < 2; ++kk) { const bf16x8_t av = *(const bf16x8_t*)(A + (16 * mt + r16) * 72 + 32 * kk + 8 * kq);
; #pragma unroll
;         for (int i = 0; i < 2; ++i) { const bf16x8_t bv = *(const bf16x8_t*)(Bt + (16 * (ntb + i) + r16) * 72 + 32 * kk + 8 * kq); acc[i] = __builtin_amdgcn_mfma_f32_16x16x32_bf16(av, bv, acc[i], 0, 0, 0); } }
; }
; template <bool PA> ...
;     ...
;                   mm2(za, MAT(4), w2T, mt, ntb, r16, kq); mm2(xa, MAT(5), a2T, mt, ntb, r16, kq);
	s_mov_b32 s0, 0xff0000
	s_mov_b32 s1, 0xff
	v_cndmask_b32_e64 v201, 0, 16, s[0:1]
	s_mov_b32 s0, 0xff000000
	s_mov_b32 s1, 0xff00
	v_cndmask_b32_e64 v252, 0, 16, s[0:1]
	v_sub_u32_e32 v201, v201, v252
	v_add_u32_e32 v104, v104, v201
	s_mov_b32 s0, 0xff0
	s_mov_b32 s1, 0xff0
	v_cndmask_b32_e64 v201, 0, 16, s[0:1]
	s_mov_b32 s0, 0xff00000
	s_mov_b32 s1, 0xff00000
	v_cndmask_b32_e64 v252, 0, 16, s[0:1]
	v_sub_u32_e32 v201, v201, v252
	v_add_u32_e32 v105, v105, v201
	s_mov_b32 s0, 0xff0
	s_mov_b32 s1, 0xff0
	v_cndmask_b32_e64 v201, 0, 16, s[0:1]
	s_mov_b32 s0, 0xff00000
	s_mov_b32 s1, 0xff00000
	v_cndmask_b32_e64 v252, 0, 16, s[0:1]
	v_sub_u32_e32 v201, v201, v252
	v_add_u32_e32 v106, v106, v201
	s_mov_b32 s0, 0xff0
	s_mov_b32 s1, 0xff0
	v_cndmask_b32_e64 v201, 0, 16, s[0:1]
	s_mov_b32 s0, 0xff00000
	s_mov_b32 s1, 0xff00000
	v_cndmask_b32_e64 v252, 0, 16, s[0:1]
	v_sub_u32_e32 v201, v201, v252
	v_add_u32_e32 v107, v107, v201
	s_mov_b32 s0, 0xff00ff0
	s_mov_b32 s1, 0x0
	v_cndmask_b32_e64 v201, 0, 16, s[0:1]
	s_mov_b32 s0, 0x0
	s_mov_b32 s1, 0xff00ff0
	v_cndmask_b32_e64 v252, 0, 16, s[0:1]
	v_sub_u32_e32 v201, v201, v252
	v_add_u32_e32 v108, v108, v201
	s_mov_b32 s0, 0xff00ff0
	s_mov_b32 s1, 0x0
	v_cndmask_b32_e64 v201, 0, 16, s[0:1]
	s_mov_b32 s0, 0x0
	s_mov_b32 s1, 0xff00ff0
	v_cndmask_b32_e64 v252, 0, 16, s[0:1]
	v_sub_u32_e32 v201, v201, v252
	v_add_u32_e32 v109, v109, v201
	s_mov_b32 s0, 0xff0
	s_mov_b32 s1, 0xff0
	v_cndmask_b32_e64 v201, 0, 16, s[0:1]
	s_mov_b32 s0, 0xff00000
	s_mov_b32 s1, 0xff00000
	v_cndmask_b32_e64 v252, 0, 16, s[0:1]
	v_sub_u32_e32 v201, v201, v252
	v_add_u32_e32 v110, v110, v201
	s_mov_b32 s0, 0xff00ff0
	s_mov_b32 s1, 0x0
	v_cndmask_b32_e64 v201, 0, 16, s[0:1]
	s_mov_b32 s0, 0x0
	s_mov_b32 s1, 0xff00ff0
	v_cndmask_b32_e64 v252, 0, 16, s[0:1]
	v_sub_u32_e32 v201, v201, v252
	v_add_u32_e32 v111, v111, v201
	s_mov_b32 s0, 0xff0
	s_mov_b32 s1, 0xff0
	v_cndmask_b32_e64 v201, 0, 16, s[0:1]
	s_mov_b32 s0, 0xff00000
	s_mov_b32 s1, 0xff00000
	v_cndmask_b32_e64 v252, 0, 16, s[0:1]
	v_sub_u32_e32 v201, v201, v252
	v_add_u32_e32 v112, v112, v201
	s_mov_b32 s0, 0xff0
	s_mov_b32 s1, 0xff0
	v_cndmask_b32_e64 v201, 0, 16, s[0:1]
	s_mov_b32 s0, 0xff00000
	s_mov_b32 s1, 0xff00000
	v_cndmask_b32_e64 v252, 0, 16, s[0:1]
	v_sub_u32_e32 v201, v201, v252
	v_add_u32_e32 v113, v113, v201
	s_mov_b32 s0, 0xff0
	s_mov_b32 s1, 0xff0
	v_cndmask_b32_e64 v201, 0, 16, s[0:1]
	s_mov_b32 s0, 0xff00000
	s_mov_b32 s1, 0xff00000
	v_cndmask_b32_e64 v252, 0, 16, s[0:1]
	v_sub_u32_e32 v201, v201, v252
	v_add_u32_e32 v114, v114, v201
	s_mov_b32 s0, 0xff0
	s_mov_b32 s1, 0xff0
	v_cndmask_b32_e64 v201, 0, 16, s[0:1]
	s_mov_b32 s0, 0xff00000
	s_mov_b32 s1, 0xff00000
	v_cndmask_b32_e64 v252, 0, 16, s[0:1]
	v_sub_u32_e32 v201, v201, v252
	v_add_u32_e32 v115, v115, v201
	s_mov_b32 s0, 0xaaaaaaaa
	s_mov_b32 s1, 0xaaaaaaaa
	s_bitcmp1_b32 s9, 6
	s_cmov_b32 s0, 0x0
	s_cmov_b32 s1, 0x0
	v_cndmask_b32_e64 v201, 0, 16, s[0:1]
	s_mov_b32 s0, 0x0
	s_mov_b32 s1, 0x0
	s_bitcmp1_b32 s9, 6
	s_cmov_b32 s0, 0xaaaaaaaa
	s_cmov_b32 s1, 0xaaaaaaaa
	v_cndmask_b32_e64 v252, 0, 16, s[0:1]
	v_sub_u32_e32 v201, v201, v252
	v_add_u32_e32 v117, v117, v201
	s_mov_b32 s0, 0x55555555
	s_mov_b32 s1, 0x55555555
	s_bitcmp1_b32 s9, 6
	s_cmov_b32 s0, 0x0
	s_cmov_b32 s1, 0x0
	v_cndmask_b32_e64 v201, 0, 16, s[0:1]
	s_mov_b32 s0, 0x0
	s_mov_b32 s1, 0x0
	s_bitcmp1_b32 s9, 6
	s_cmov_b32 s0, 0x55555555
	s_cmov_b32 s1, 0x55555555
	v_cndmask_b32_e64 v252, 0, 16, s[0:1]
	v_sub_u32_e32 v201, v201, v252
	v_add_u32_e32 v176, v176, v201
	s_mov_b32 s0, 0x55555555
	s_mov_b32 s1, 0x55555555
	s_bitcmp1_b32 s9, 6
	s_cmov_b32 s0, 0x0
	s_cmov_b32 s1, 0x0
	v_cndmask_b32_e64 v201, 0, 16, s[0:1]
	s_mov_b32 s0, 0x0
	s_mov_b32 s1, 0x0
	s_bitcmp1_b32 s9, 6
	s_cmov_b32 s0, 0x55555555
	s_cmov_b32 s1, 0x55555555
	v_cndmask_b32_e64 v252, 0, 16, s[0:1]
	v_sub_u32_e32 v201, v201, v252
	v_add_u32_e32 v118, v118, v201
	v_readfirstlane_b32 s9, v202
	s_mov_b32 s0, 0xff0
	s_mov_b32 s1, 0xff0
	v_cndmask_b32_e64 v177, 0, 16, s[0:1]
	s_mov_b32 s0, 0xff00000
	s_mov_b32 s1, 0xff00000
	v_cndmask_b32_e64 v200, 0, 16, s[0:1]
	v_sub_u32_e32 v177, v177, v200
	v_add_u32_e32 v93, v93, v177
	s_mov_b32 s0, 0xff0
	s_mov_b32 s1, 0xff0
	v_cndmask_b32_e64 v177, 0, 16, s[0:1]
	s_mov_b32 s0, 0xff00000
	s_mov_b32 s1, 0xff00000
	v_cndmask_b32_e64 v200, 0, 16, s[0:1]
	v_sub_u32_e32 v177, v177, v200
	v_add_u32_e32 v94, v94, v177
	s_mov_b32 s2, s96
	s_branch .LBB0_129

; __device__ __forceinline__ unsigned f2bf(float f) { return pk2(f, 0.f) & 0xffffu; }
; template <bool PA> ...
;     ...
;         for (int i = tid; i < 4096; i += 512) { const int l = i >> 6, cc = i & 63; w2T[cc * 72 + l] = (bf16)f2bf(w2[(size_t)l * 1024 + head * 64 + cc]); a2T[cc * 72 + l] = (bf16)f2bf(a2[(size_t)l * 1024 + head * 64 + cc]); }
.LBB0_145:
	v_ashrrev_i32_e32 v4, 6, v2
	v_ashrrev_i32_e32 v5, 31, v4
	v_lshlrev_b64 v[6:7], 12, v[4:5]
	v_lshl_or_b32 v6, v0, 2, v6
	v_add_u32_e32 v4, v4, v116
	v_lshl_add_u32 v8, v4, 1, 0
	v_add_u32_e32 v222, 0x1d400, v8
	v_add_u32_e32 v223, 0x1f800, v8
	v_lshl_add_u64 v[220:221], s[20:21], 0, v[6:7]
	global_load_dword v204, v[220:221], off
	v_lshl_add_u64 v[220:221], s[92:93], 0, v[6:7]
	global_load_dword v205, v[220:221], off
	s_add_u32 s20, s20, 0x8000
	s_addc_u32 s21, s21, 0
	s_add_u32 s92, s92, 0x8000
	s_addc_u32 s93, s93, 0
	v_lshl_add_u64 v[220:221], s[20:21], 0, v[6:7]
	global_load_dword v206, v[220:221], off
	v_lshl_add_u64 v[220:221], s[92:93], 0, v[6:7]
	global_load_dword v207, v[220:221], off
	s_add_u32 s20, s20, 0x8000
	s_addc_u32 s21, s21, 0
	s_add_u32 s92, s92, 0x8000
	s_addc_u32 s93, s93, 0
	v_lshl_add_u64 v[220:221], s[20:21], 0, v[6:7]
	global_load_dword v208, v[220:221], off
	v_lshl_add_u64 v[220:221], s[92:93], 0, v[6:7]
	global_load_dword v209, v[220:221], off
	s_add_u32 s20, s20, 0x8000
	s_addc_u32 s21, s21, 0
	s_add_u32 s92, s92, 0x8000
	s_addc_u32 s93, s93, 0
	v_lshl_add_u64 v[220:221], s[20:21], 0, v[6:7]
	global_load_dword v210, v[220:221], off
	v_lshl_add_u64 v[220:221], s[92:93], 0, v[6:7]
	global_load_dword v211, v[220:221], off
	s_add_u32 s20, s20, 0x8000
	s_addc_u32 s21, s21, 0
	s_add_u32 s92, s92, 0x8000
	s_addc_u32 s93, s93, 0
	v_lshl_add_u64 v[220:221], s[20:21], 0, v[6:7]
	global_load_dword v212, v[220:221], off
	v_lshl_add_u64 v[220:221], s[92:93], 0, v[6:7]
	global_load_dword v213, v[220:221], off
	s_add_u32 s20, s20, 0x8000
	s_addc_u32 s21, s21, 0
	s_add_u32 s92, s92, 0x8000
	s_addc_u32 s93, s93, 0
	v_lshl_add_u64 v[220:221], s[20:21], 0, v[6:7]
	global_load_dword v214, v[220:221], off
	v_lshl_add_u64 v[220:221], s[92:93], 0, v[6:7]
	global_load_dword v215, v[220:221], off
	s_add_u32 s20, s20, 0x8000
	s_addc_u32 s21, s21, 0
	s_add_u32 s92, s92, 0x8000
	s_addc_u32 s93, s93, 0
	v_lshl_add_u64 v[220:221], s[20:21], 0, v[6:7]
	global_load_dword v216, v[220:221], off
	v_lshl_add_u64 v[220:221], s[92:93], 0, v[6:7]
	global_load_dword v217, v[220:221], off
	s_add_u32 s20, s20, 0x8000
	s_addc_u32 s21, s21, 0
	s_add_u32 s92, s92, 0x8000
	s_addc_u32 s93, s93, 0
	v_lshl_add_u64 v[220:221], s[20:21], 0, v[6:7]
	global_load_dword v218, v[220:221], off
	v_lshl_add_u64 v[220:221], s[92:93], 0, v[6:7]
	global_load_dword v219, v[220:221], off
	s_sub_u32 s20, s20, 0x38000
	s_subb_u32 s21, s21, 0
	s_sub_u32 s92, s92, 0x38000
	s_subb_u32 s93, s93, 0
	s_waitcnt vmcnt(15)
	v_cvt_pk_bf16_f32 v3, v204, s0
	v_and_b32_e32 v200, 15, v203
	v_add_u32_e32 v200, 4, v200
	v_and_b32_e32 v200, 8, v200
	v_lshlrev_b32_e32 v200, 1, v200
	v_add_u32_e32 v194, v222, v200
	v_sub_u32_e32 v195, v222, v200
	v_add_u32_e32 v177, v223, v200
	v_sub_u32_e32 v200, v223, v200
	ds_write_b16 v194, v3 offset:0
	s_waitcnt vmcnt(14)
	v_cvt_pk_bf16_f32 v9, v205, s0
	ds_write_b16 v177, v9 offset:0
	s_waitcnt vmcnt(13)
	v_cvt_pk_bf16_f32 v3, v206, s0
	ds_write_b16 v195, v3 offset:16
	s_waitcnt vmcnt(12)
	v_cvt_pk_bf16_f32 v9, v207, s0
	ds_write_b16 v200, v9 offset:16
	s_waitcnt vmcnt(11)
	v_cvt_pk_bf16_f32 v3, v208, s0
	ds_write_b16 v194, v3 offset:32
	s_waitcnt vmcnt(10)
	v_cvt_pk_bf16_f32 v9, v209, s0
	ds_write_b16 v177, v9 offset:32
	s_waitcnt vmcnt(9)
	v_cvt_pk_bf16_f32 v3, v210, s0
	ds_write_b16 v195, v3 offset:48
	s_waitcnt vmcnt(8)
	v_cvt_pk_bf16_f32 v9, v211, s0
	ds_write_b16 v200, v9 offset:48
	s_waitcnt vmcnt(7)
	v_cvt_pk_bf16_f32 v3, v212, s0
	ds_write_b16 v194, v3 offset:64
	s_waitcnt vmcnt(6)
	v_cvt_pk_bf16_f32 v9, v213, s0
	ds_write_b16 v177, v9 offset:64
	s_waitcnt vmcnt(5)
	v_cvt_pk_bf16_f32 v3, v214, s0
	ds_write_b16 v195, v3 offset:80
	s_waitcnt vmcnt(4)
	v_cvt_pk_bf16_f32 v9, v215, s0
	ds_write_b16 v200, v9 offset:80
	s_waitcnt vmcnt(3)
	v_cvt_pk_bf16_f32 v3, v216, s0
	ds_write_b16 v194, v3 offset:96
	s_waitcnt vmcnt(2)
	v_cvt_pk_bf16_f32 v9, v217, s0
	ds_write_b16 v177, v9 offset:96
	s_waitcnt vmcnt(1)
	v_cvt_pk_bf16_f32 v3, v218, s0
	ds_write_b16 v195, v3 offset:112
	s_waitcnt vmcnt(0)
	v_cvt_pk_bf16_f32 v9, v219, s0
	ds_write_b16 v200, v9 offset:112

; __device__ __forceinline__ unsigned f2bf(float f) { return pk2(f, 0.f) & 0xffffu; }
; template <bool PA> ...
;     bf16* M = (bf16*)lds;
;     ...
;     bf16* w2T = MAT(13); bf16* a2T = MAT(14); float* wc = (float*)MAT(15); float* cst = wc + 64;
;     float* zbuf = (float*)MAT(0); float* abuf = zbuf + 4096;
;     float* cumb = (float*)MAT(10); float* segtot = cumb + 4096;
;     const int nch = slab == 0 ? 129 : 257, G = slab == 0 ? 4 : 8, nitems = 256, NCHA = nch;
;     const int lane = tid & 63, wave = tid >> 6, r16 = lane & 15, kq = lane >> 4, mt = wave >> 1, ntb = 2 * (wave & 1);
;     const int j = tid >> 3, part = tid & 7, c8 = part * 8;
;     const int tunit = ((j >> 3) + 1) * (4 * (j >> 3) + (j & 7)) + part; const bool tlow = part <= (j >> 3);
;     for (int item = blockIdx.x; item < nitems; item += gridDim.x) {
;         const int g = item % G, strm = item / G; const int p0 = g == 0 ? 0 : 1 + 32 * g, p1 = 33 + 32 * g;
;         const bool haveT = !PA;
;         const int d = strm & 1, head = (strm >> 1) & 15, sq = strm >> 5; const int seqbase = sq * 8256; const int hc8 = head * 64 + c8;
;         bf16* Op = d ? OBb : OFb;
;         const float* w0 = a->in[15] + d * 1024; const float* w2 = a->in[17] + (size_t)d * 64 * 1024; const float* a0 = a->in[18] + d * 1024; const float* a2 = a->in[20] + (size_t)d * 64 * 1024;
;         __syncthreads();
;         if (tid < 320) { const int wch = tid >> 6, cc = tid & 63; const float* src = wch == 0 ? w0 : (wch == 1 ? a0 : (wch == 2 ? a->in[23] : (wch == 3 ? a->in[24] : a->in[25]))); cst[tid] = src[head * 64 + cc]; }
;         for (int i = tid; i < 4096; i += 512) { const int l = i >> 6, cc = i & 63; w2T[cc * 72 + l] = (bf16)f2bf(w2[(size_t)l * 1024 + head * 64 + cc]); a2T[cc * 72 + l] = (bf16)f2bf(a2[(size_t)l * 1024 + head * 64 + cc]); }
;         f32x4_t Sacc[2], S2acc[2]; Sacc[0] = (f32x4_t){0.f, 0.f, 0.f, 0.f}; Sacc[1] = Sacc[0];
; #pragma unroll
;         for (int i = 0; i < 2; ++i)
; #pragma unroll
;             for (int e = 0; e < 4; ++e) S2acc[i][e] = (16 * mt + 4 * kq + e == 16 * (ntb + i) + r16) ? 1.f : 0.f;
.LBB0_190:
	s_andn2_b64 vcc, exec, s[0:1]
	s_cbranch_vccnz .LBB0_250
	v_readlane_b32 s0, v253, 2
	v_readlane_b32 s1, v253, 3
	s_andn2_b64 vcc, exec, s[0:1]
	s_cbranch_vccnz .LBB0_250
	v_ashrrev_i32_e32 v103, 6, v202
	v_writelane_b32 v255, s70, 18
	v_ashrrev_i32_e32 v104, 3, v202
	v_lshlrev_b32_e32 v0, 1, v103
	v_writelane_b32 v255, s71, 19
	v_and_b32_e32 v11, 2, v0
	v_and_b32_e32 v0, 7, v104
	v_lshl_add_u32 v0, v103, 2, v0
	v_readlane_b32 s12, v255, 5
	v_mad_u64_u32 v[2:3], s[8:9], v0, v103, v[0:1]
	v_readlane_b32 s13, v255, 6
	s_load_dwordx2 s[8:9], s[12:13], 0x78
	v_and_b32_e32 v9, 7, v203
	v_lshlrev_b32_e32 v0, 4, v9
	s_add_u32 s0, s6, 0x9a00000
	v_and_b32_e32 v5, 15, v203
	s_waitcnt lgkmcnt(0)
	v_writelane_b32 v255, s8, 32
	v_add_u32_e32 v4, 0, v0
	v_lshl_add_u64 v[6:7], s[6:7], 0, v[0:1]
	v_writelane_b32 v255, s9, 33
	s_load_dwordx4 s[8:11], s[12:13], 0x88
	s_load_dwordx2 s[38:39], s[12:13], 0xa0
	v_cmp_lt_u32_e64 s[12:13], 63, v202
	s_movk_i32 s15, 0x90
	s_addc_u32 s1, s7, 0
	v_writelane_b32 v255, s12, 20
	v_lshl_or_b32 v22, v11, 4, v5
	s_add_u32 s18, s6, 0xba80000
	v_writelane_b32 v255, s13, 21
	s_mov_b64 s[12:13], 0x730000
	v_lshl_add_u64 v[66:67], v[6:7], 0, s[12:13]
	v_mad_u64_u32 v[68:69], s[12:13], v104, s15, v[4:5]
	s_mov_b64 s[12:13], 0xb40000
	v_mul_u32_u24_e32 v23, 0x48, v22
	s_addc_u32 s19, s7, 0
	v_lshl_add_u64 v[70:71], v[6:7], 0, s[12:13]
	v_and_b32_e32 v21, 48, v203
	v_lshlrev_b32_e32 v23, 1, v23
	v_readlane_b32 s12, v254, 31
	s_add_u32 s22, s6, 0xdb00000
	v_and_b32_e32 v102, 63, v203
	v_add3_u32 v108, s12, v21, v23
	v_readlane_b32 s12, v254, 32
	s_addc_u32 s23, s7, 0
	v_bfe_u32 v3, v203, 4, 2
	v_lshlrev_b32_e32 v8, 2, v202
	v_and_b32_e32 v10, -16, v104
	v_lshlrev_b32_e32 v14, 2, v102
	v_add3_u32 v109, s12, v21, v23
	v_lshlrev_b32_e32 v24, 8, v104
	v_readlane_b32 s12, v254, 33
	s_cmp_eq_u32 s40, 0
	s_movk_i32 s2, 0x81
	v_readlane_b32 s20, v254, 26
	v_lshlrev_b32_e32 v12, 5, v9
	v_readlane_b32 s21, v254, 27
	v_lshlrev_b32_e32 v7, 3, v3
	v_add3_u32 v110, v4, v0, v24
	v_add_u32_e32 v113, s12, v8
	v_add_u32_e32 v114, s12, v14
	v_readlane_b32 s13, v254, 34
	v_lshlrev_b32_e32 v4, 1, v10
	v_readlane_b32 s12, v254, 28
	s_cselect_b32 s91, s2, 0x101
	s_movk_i32 s2, 0x140
	v_add_u32_e32 v106, s20, v8
	v_lshl_or_b32 v13, v3, 2, v10
	v_readlane_b32 s24, v254, 30
	v_bfi_b32 v6, -16, v104, v203
	v_add_u32_e32 v111, s20, v12
	v_add3_u32 v112, s21, v12, v24
	v_add_u32_e32 v115, s13, v12
	v_add_u32_e32 v8, s12, v4
	v_add_u32_e32 v10, 0x900, v23
	v_add3_u32 v126, s12, v21, v23
	v_add3_u32 v12, 0, v4, v7
	s_mov_b32 s12, 0xfc00
	v_cmp_gt_i32_e64 s[36:37], s2, v202
	s_movk_i32 s2, 0x1000
	v_lshlrev_b32_e32 v15, 1, v5
	v_mul_lo_u32 v6, v6, s15
	v_add_u32_e32 v3, 0, v21
	v_add3_u32 v120, v8, v7, v23
	v_add_u32_e32 v8, s24, v21
	v_add3_u32 v129, v12, v10, s12
	v_readlane_b32 s12, v254, 29
	s_mov_b32 s95, s40
	s_cselect_b32 s78, 4, 8
	v_cmp_gt_i32_e64 s[40:41], s2, v202
	s_add_i32 s2, 0, 0x12000
	v_add_u32_e32 v19, s21, v15
	v_add_u32_e32 v69, v3, v6
	v_mul_lo_u32 v25, v13, s15
	s_waitcnt vmcnt(0)
	v_lshlrev_b32_e32 v26, 5, v11
	v_add_u32_e32 v118, v3, v23
	v_add_u32_e32 v122, v8, v23
	v_add_u32_e32 v3, v3, v10
	v_add_u32_e32 v10, s12, v4
	v_add_u32_e32 v134, v8, v6
	v_cmp_eq_u32_e64 s[44:45], v13, v22
	v_or_b32_e32 v8, 1, v13
	v_add3_u32 v121, v19, v25, v26
	v_add3_u32 v130, v10, v7, v23
	v_add_u32_e32 v10, s2, v4
	v_add_u32_e32 v4, s24, v4
	v_cndmask_b32_e64 v136, 0, 1.0, s[44:45]
	v_cmp_eq_u32_e64 s[44:45], v8, v22
	v_or_b32_e32 v19, 2, v13
	v_add_u32_e32 v17, s24, v15
	v_add_u32_e32 v127, v12, v23
	v_add3_u32 v131, v10, v7, v23
	v_add3_u32 v132, s12, v21, v23
	v_add3_u32 v133, v4, v7, v23
	v_or_b32_e32 v7, 1, v11
	v_cndmask_b32_e64 v137, 0, 1.0, s[44:45]
	v_cmp_eq_u32_e64 s[44:45], v19, v22
	v_or_b32_e32 v23, 3, v13
	v_add3_u32 v117, v17, v25, v26
	v_lshl_or_b32 v17, v7, 4, v5
	v_cndmask_b32_e64 v138, 0, 1.0, s[44:45]
	v_cmp_eq_u32_e64 s[44:45], v23, v22
	v_add_u32_e32 v16, 0, v15
	v_add_u32_e32 v18, s2, v15
	v_cndmask_b32_e64 v139, 0, 1.0, s[44:45]
	v_cmp_eq_u32_e64 s[44:45], v13, v17
	v_add_u32_e32 v20, s21, v14
	v_add3_u32 v116, v16, v25, v26
	v_add3_u32 v119, v18, v25, v26
	v_add3_u32 v125, s2, v6, v21
	v_add3_u32 v128, s21, v6, v21
	v_lshlrev_b32_e32 v6, 6, v13
	v_cndmask_b32_e64 v140, 0, 1.0, s[44:45]
	v_cmp_eq_u32_e64 s[44:45], v8, v17
	v_lshlrev_b32_e32 v14, 6, v8
	v_lshlrev_b32_e32 v16, 6, v19
	v_lshlrev_b32_e32 v18, 6, v23
	v_or_b32_e32 v4, v17, v6
	v_cndmask_b32_e64 v141, 0, 1.0, s[44:45]
	v_cmp_eq_u32_e64 s[44:45], v19, v17
	v_or_b32_e32 v6, v22, v6
	v_or_b32_e32 v8, v14, v22
	v_or_b32_e32 v10, v16, v22
	v_or_b32_e32 v12, v18, v22
	v_cmp_lt_i32_e64 s[58:59], v22, v13
	v_cmp_gt_i32_e64 s[60:61], v22, v13
	v_cmp_lt_i32_e64 s[62:63], v22, v19
	v_cmp_lt_i32_e64 s[64:65], v22, v23
	v_lshlrev_b32_e32 v22, 6, v11
	v_cvt_f32_ubyte0_e32 v11, s78
	v_cndmask_b32_e64 v142, 0, 1.0, s[44:45]
	v_cmp_eq_u32_e64 s[44:45], v23, v17
	v_or_b32_e32 v14, v17, v14
	v_or_b32_e32 v16, v17, v16
	v_or_b32_e32 v18, v17, v18
	v_cmp_lt_i32_e64 s[66:67], v17, v13
	v_cmp_gt_i32_e64 s[68:69], v17, v13
	v_cmp_lt_i32_e64 s[70:71], v17, v19
	v_cmp_lt_i32_e64 s[72:73], v17, v23
	v_rcp_iflag_f32_e32 v17, v11
	v_lshlrev_b32_e32 v105, 3, v9
	v_cmp_le_i32_e32 vcc, v9, v103
	v_add_lshl_u32 v2, v2, v9, 3
	v_mul_u32_u24_e32 v9, 0x240, v9
	v_lshlrev_b32_e32 v24, 1, v104
	v_lshlrev_b32_e32 v9, 1, v9
	v_mul_f32_e32 v17, 0x4f7ffffe, v17
	v_add3_u32 v154, 0, v24, v9
	v_cvt_u32_f32_e32 v24, v17
	v_add_u32_e32 v9, s2, v25
	s_sub_i32 s2, 0, s78
	v_add_u32_e32 v123, 0xfc00, v3
	v_readfirstlane_b32 s12, v24
	s_mul_i32 s2, s2, s12
	v_add_u32_e32 v124, 0xfc40, v3
	v_ashrrev_i32_e32 v3, 31, v2
	v_add3_u32 v155, v9, v15, v26
	v_add_u32_e32 v9, 0, v25
	s_mul_hi_u32 s2, s12, s2
	v_lshlrev_b32_e32 v0, 11, v103
	v_lshl_add_u32 v21, v5, 2, s13
	v_ashrrev_i32_e32 v5, 31, v4
	s_waitcnt vmcnt(47)
; __device__ __forceinline__ unsigned f2bf(float f) { return pk2(f, 0.f) & 0xffffu; }
; template <bool PA> ...
;     ...
;     bf16* w2T = MAT(13); bf16* a2T = MAT(14); float* wc = (float*)MAT(15); float* cst = wc + 64;
;     float* zbuf = (float*)MAT(0); float* abuf = zbuf + 4096;
;     float* cumb = (float*)MAT(10); float* segtot = cumb + 4096;
;     const int nch = slab == 0 ? 129 : 257, G = slab == 0 ? 4 : 8, nitems = 256, NCHA = nch;
;     const int lane = tid & 63, wave = tid >> 6, r16 = lane & 15, kq = lane >> 4, mt = wave >> 1, ntb = 2 * (wave & 1);
;     const int j = tid >> 3, part = tid & 7, c8 = part * 8;
;     const int tunit = ((j >> 3) + 1) * (4 * (j >> 3) + (j & 7)) + part; const bool tlow = part <= (j >> 3);
;     for (int item = blockIdx.x; item < nitems; item += gridDim.x) {
;         const int g = item % G, strm = item / G; const int p0 = g == 0 ? 0 : 1 + 32 * g, p1 = 33 + 32 * g;
;         const bool haveT = !PA;
;         const int d = strm & 1, head = (strm >> 1) & 15, sq = strm >> 5; const int seqbase = sq * 8256; const int hc8 = head * 64 + c8;
;         bf16* Op = d ? OBb : OFb;
;         const float* w0 = a->in[15] + d * 1024; const float* w2 = a->in[17] + (size_t)d * 64 * 1024; const float* a0 = a->in[18] + d * 1024; const float* a2 = a->in[20] + (size_t)d * 64 * 1024;
;         __syncthreads();
;         if (tid < 320) { const int wch = tid >> 6, cc = tid & 63; const float* src = wch == 0 ? w0 : (wch == 1 ? a0 : (wch == 2 ? a->in[23] : (wch == 3 ? a->in[24] : a->in[25]))); cst[tid] = src[head * 64 + cc]; }
;         for (int i = tid; i < 4096; i += 512) { const int l = i >> 6, cc = i & 63; w2T[cc * 72 + l] = (bf16)f2bf(w2[(size_t)l * 1024 + head * 64 + cc]); a2T[cc * 72 + l] = (bf16)f2bf(a2[(size_t)l * 1024 + head * 64 + cc]); }
;         f32x4_t Sacc[2], S2acc[2]; Sacc[0] = (f32x4_t){0.f, 0.f, 0.f, 0.f}; Sacc[1] = Sacc[0];
; #pragma unroll
;         for (int i = 0; i < 2; ++i)
; #pragma unroll
;             for (int e = 0; e < 4; ++e) S2acc[i][e] = (16 * mt + 4 * kq + e == 16 * (ntb + i) + r16) ? 1.f : 0.f;
	v_add3_u32 v156, v9, v15, v26
	v_lshlrev_b32_e32 v23, 6, v7
	v_ashrrev_i32_e32 v7, 31, v6
	v_ashrrev_i32_e32 v9, 31, v8
	v_ashrrev_i32_e32 v11, 31, v10
	v_ashrrev_i32_e32 v13, 31, v12
	v_ashrrev_i32_e32 v15, 31, v14
	v_ashrrev_i32_e32 v17, 31, v16
	v_ashrrev_i32_e32 v19, 31, v18
	s_add_i32 s2, s12, s2
	v_lshl_add_u64 v[2:3], v[2:3], 1, s[6:7]
	s_mov_b64 s[12:13], 0x2000000
	v_sub_u32_e32 v107, 63, v104
	v_cmp_eq_u32_e64 s[42:43], 63, v104
	v_mul_u32_u24_e32 v135, 0x48, v102
	v_cndmask_b32_e64 v143, 0, 1.0, s[44:45]
	v_lshl_add_u32 v144, v6, 2, 0
	v_lshl_add_u32 v145, v8, 2, 0
	v_lshl_add_u32 v148, v10, 2, 0
	v_lshl_add_u32 v149, v12, 2, 0
	v_lshl_add_u32 v150, v4, 2, 0
	v_lshl_add_u32 v151, v14, 2, 0
	v_lshl_add_u32 v152, v16, 2, 0
	v_lshl_add_u32 v153, v18, 2, 0
	v_cmp_lt_i32_e64 s[44:45], 0, v103
	v_cmp_lt_i32_e64 s[46:47], 1, v103
	v_cmp_lt_i32_e64 s[48:49], 2, v103
	v_cmp_lt_i32_e64 s[50:51], 3, v103
	v_cmp_lt_i32_e64 s[52:53], 4, v103
	v_cmp_lt_i32_e64 s[54:55], 5, v103
	v_cmp_lt_i32_e64 s[56:57], 6, v103
	v_lshl_add_u64 v[72:73], v[2:3], 0, s[12:13]
	s_add_i32 s79, s91, -1
	s_waitcnt vmcnt(46)
	v_add_u32_e32 v157, v21, v22
	v_add_u32_e32 v158, v21, v23
	v_lshlrev_b64 v[74:75], 2, v[6:7]
	v_lshlrev_b64 v[76:77], 2, v[8:9]
	v_lshlrev_b64 v[78:79], 2, v[10:11]
	v_lshlrev_b64 v[80:81], 2, v[12:13]
	v_lshlrev_b64 v[82:83], 2, v[4:5]
	v_lshlrev_b64 v[84:85], 2, v[14:15]
	v_lshlrev_b64 v[86:87], 2, v[16:17]
	v_lshlrev_b64 v[88:89], 2, v[18:19]
	s_waitcnt vmcnt(45)
	v_add_u32_e32 v159, v20, v0
	v_readfirstlane_b32 s15, v202
	v_mov_b32_e32 v185, v154
	s_mov_b32 s12, 0x0
	s_mov_b32 s13, 0x55555555
	s_bitcmp1_b32 s15, 6
	s_cmov_b32 s12, 0x55555555
	s_cmov_b32 s13, 0x0
	v_cndmask_b32_e64 v201, 0, 16, s[12:13]
	s_mov_b32 s12, 0x0
	s_mov_b32 s13, 0xaaaaaaaa
	s_bitcmp1_b32 s15, 6
	s_cmov_b32 s12, 0xaaaaaaaa
	s_cmov_b32 s13, 0x0
	v_cndmask_b32_e64 v252, 0, 16, s[12:13]
	v_sub_u32_e32 v201, v201, v252
	v_add_u32_e32 v68, v68, v201
	s_mov_b32 s12, 0xff0
	s_mov_b32 s13, 0xff0
	v_cndmask_b32_e64 v201, 0, 16, s[12:13]
	s_mov_b32 s12, 0xff00000
	s_mov_b32 s13, 0xff00000
	v_cndmask_b32_e64 v252, 0, 16, s[12:13]
	v_sub_u32_e32 v201, v201, v252
	v_add_u32_e32 v69, v69, v201
	s_mov_b32 s12, 0xff0000
	s_mov_b32 s13, 0xff
	v_cndmask_b32_e64 v201, 0, 16, s[12:13]
	s_mov_b32 s12, 0xff000000
	s_mov_b32 s13, 0xff00
	v_cndmask_b32_e64 v252, 0, 16, s[12:13]
	v_sub_u32_e32 v201, v201, v252
	v_add_u32_e32 v116, v116, v201
	s_mov_b32 s12, 0xff0000
	s_mov_b32 s13, 0xff
	v_cndmask_b32_e64 v201, 0, 16, s[12:13]
	s_mov_b32 s12, 0xff000000
	s_mov_b32 s13, 0xff00
	v_cndmask_b32_e64 v252, 0, 16, s[12:13]
	v_sub_u32_e32 v201, v201, v252
	v_add_u32_e32 v117, v117, v201
	s_mov_b32 s12, 0xff0
	s_mov_b32 s13, 0xff0
	v_cndmask_b32_e64 v201, 0, 16, s[12:13]
	s_mov_b32 s12, 0xff00000
	s_mov_b32 s13, 0xff00000
	v_cndmask_b32_e64 v252, 0, 16, s[12:13]
	v_sub_u32_e32 v201, v201, v252
	v_add_u32_e32 v118, v118, v201
	s_mov_b32 s12, 0xff0000
	s_mov_b32 s13, 0xff
	v_cndmask_b32_e64 v201, 0, 16, s[12:13]
	s_mov_b32 s12, 0xff000000
	s_mov_b32 s13, 0xff00
	v_cndmask_b32_e64 v252, 0, 16, s[12:13]
	v_sub_u32_e32 v201, v201, v252
	v_add_u32_e32 v119, v119, v201
	s_mov_b32 s12, 0xff00ff0
	s_mov_b32 s13, 0x0
	v_cndmask_b32_e64 v201, 0, 16, s[12:13]
	s_mov_b32 s12, 0x0
	s_mov_b32 s13, 0xff00ff0
	v_cndmask_b32_e64 v252, 0, 16, s[12:13]
	v_sub_u32_e32 v201, v201, v252
	v_add_u32_e32 v120, v120, v201
	s_mov_b32 s12, 0xff0000
	s_mov_b32 s13, 0xff
	v_cndmask_b32_e64 v201, 0, 16, s[12:13]
	s_mov_b32 s12, 0xff000000
	s_mov_b32 s13, 0xff00
	v_cndmask_b32_e64 v252, 0, 16, s[12:13]
	v_sub_u32_e32 v201, v201, v252
	v_add_u32_e32 v121, v121, v201
	s_mov_b32 s12, 0xff0
	s_mov_b32 s13, 0xff0
	v_cndmask_b32_e64 v201, 0, 16, s[12:13]
	s_mov_b32 s12, 0xff00000
	s_mov_b32 s13, 0xff00000
	v_cndmask_b32_e64 v252, 0, 16, s[12:13]
	v_sub_u32_e32 v201, v201, v252
	v_add_u32_e32 v122, v122, v201
	s_mov_b32 s12, 0xff0
	s_mov_b32 s13, 0xff0
	v_cndmask_b32_e64 v201, 0, 16, s[12:13]
	s_mov_b32 s12, 0xff00000
	s_mov_b32 s13, 0xff00000
	v_cndmask_b32_e64 v252, 0, 16, s[12:13]
	v_sub_u32_e32 v201, v201, v252
	v_add_u32_e32 v123, v123, v201
	s_mov_b32 s12, 0xff0
	s_mov_b32 s13, 0xff0
	v_cndmask_b32_e64 v201, 0, 16, s[12:13]
	s_mov_b32 s12, 0xff00000
	s_mov_b32 s13, 0xff00000
	v_cndmask_b32_e64 v252, 0, 16, s[12:13]
; __device__ __forceinline__ void mm2(f32x4_t (&acc)[2], const bf16* A, const bf16* Bt, int mt, int ntb, int r16, int kq) {
; #pragma unroll
;     for (int kk = 0; kk < 2; ++kk) { const bf16x8_t av = *(const bf16x8_t*)(A + (16 * mt + r16) * 72 + 32 * kk + 8 * kq);
; #pragma unroll
;         for (int i = 0; i < 2; ++i) { const bf16x8_t bv = *(const bf16x8_t*)(Bt + (16 * (ntb + i) + r16) * 72 + 32 * kk + 8 * kq); acc[i] = __builtin_amdgcn_mfma_f32_16x16x32_bf16(av, bv, acc[i], 0, 0, 0); } }
; }
; template <bool PA> ...
;     ...
;                   mm2(za, MAT(4), w2T, mt, ntb, r16, kq); mm2(xa, MAT(5), a2T, mt, ntb, r16, kq);
	v_sub_u32_e32 v201, v201, v252
	v_add_u32_e32 v124, v124, v201
	s_mov_b32 s12, 0xff0
	s_mov_b32 s13, 0xff0
	v_cndmask_b32_e64 v201, 0, 16, s[12:13]
	s_mov_b32 s12, 0xff00000
	s_mov_b32 s13, 0xff00000
	v_cndmask_b32_e64 v252, 0, 16, s[12:13]
	v_sub_u32_e32 v201, v201, v252
	v_add_u32_e32 v125, v125, v201
	s_mov_b32 s12, 0xff0
	s_mov_b32 s13, 0xff0
	v_cndmask_b32_e64 v201, 0, 16, s[12:13]
	s_mov_b32 s12, 0xff00000
	s_mov_b32 s13, 0xff00000
	v_cndmask_b32_e64 v252, 0, 16, s[12:13]
	v_sub_u32_e32 v201, v201, v252
	v_add_u32_e32 v126, v126, v201
	s_mov_b32 s12, 0xff00ff0
	s_mov_b32 s13, 0x0
	v_cndmask_b32_e64 v201, 0, 16, s[12:13]
	s_mov_b32 s12, 0x0
	s_mov_b32 s13, 0xff00ff0
	v_cndmask_b32_e64 v252, 0, 16, s[12:13]
	v_sub_u32_e32 v201, v201, v252
	v_add_u32_e32 v127, v127, v201
	s_mov_b32 s12, 0xff0
	s_mov_b32 s13, 0xff0
	v_cndmask_b32_e64 v201, 0, 16, s[12:13]
	s_mov_b32 s12, 0xff00000
	s_mov_b32 s13, 0xff00000
	v_cndmask_b32_e64 v252, 0, 16, s[12:13]
	v_sub_u32_e32 v201, v201, v252
	v_add_u32_e32 v128, v128, v201
	s_mov_b32 s12, 0xff00ff0
	s_mov_b32 s13, 0x0
	v_cndmask_b32_e64 v201, 0, 16, s[12:13]
	s_mov_b32 s12, 0x0
	s_mov_b32 s13, 0xff00ff0
	v_cndmask_b32_e64 v252, 0, 16, s[12:13]
	v_sub_u32_e32 v201, v201, v252
	v_add_u32_e32 v129, v129, v201
	s_mov_b32 s12, 0xff00ff0
	s_mov_b32 s13, 0x0
	v_cndmask_b32_e64 v201, 0, 16, s[12:13]
	s_mov_b32 s12, 0x0
	s_mov_b32 s13, 0xff00ff0
	v_cndmask_b32_e64 v252, 0, 16, s[12:13]
	v_sub_u32_e32 v201, v201, v252
	v_add_u32_e32 v130, v130, v201
	s_mov_b32 s12, 0xff00ff0
	s_mov_b32 s13, 0x0
	v_cndmask_b32_e64 v201, 0, 16, s[12:13]
	s_mov_b32 s12, 0x0
	s_mov_b32 s13, 0xff00ff0
	v_cndmask_b32_e64 v252, 0, 16, s[12:13]
	v_sub_u32_e32 v201, v201, v252
	v_add_u32_e32 v131, v131, v201
	s_mov_b32 s12, 0xff0
	s_mov_b32 s13, 0xff0
	v_cndmask_b32_e64 v201, 0, 16, s[12:13]
	s_mov_b32 s12, 0xff00000
	s_mov_b32 s13, 0xff00000
	v_cndmask_b32_e64 v252, 0, 16, s[12:13]
	v_sub_u32_e32 v201, v201, v252
	v_add_u32_e32 v132, v132, v201
	s_mov_b32 s12, 0xff00ff0
	s_mov_b32 s13, 0x0
	v_cndmask_b32_e64 v201, 0, 16, s[12:13]
	s_mov_b32 s12, 0x0
	s_mov_b32 s13, 0xff00ff0
	v_cndmask_b32_e64 v252, 0, 16, s[12:13]
	v_sub_u32_e32 v201, v201, v252
	v_add_u32_e32 v133, v133, v201
	s_mov_b32 s12, 0xff0
	s_mov_b32 s13, 0xff0
	v_cndmask_b32_e64 v201, 0, 16, s[12:13]
	s_mov_b32 s12, 0xff00000
	s_mov_b32 s13, 0xff00000
	v_cndmask_b32_e64 v252, 0, 16, s[12:13]
	v_sub_u32_e32 v201, v201, v252
	v_add_u32_e32 v134, v134, v201
	s_mov_b32 s12, 0xaaaaaaaa
	s_mov_b32 s13, 0xaaaaaaaa
	s_bitcmp1_b32 s15, 6
	s_cmov_b32 s12, 0x0
	s_cmov_b32 s13, 0x0
	v_cndmask_b32_e64 v201, 0, 16, s[12:13]
	s_mov_b32 s12, 0x0
	s_mov_b32 s13, 0x0
	s_bitcmp1_b32 s15, 6
	s_cmov_b32 s12, 0xaaaaaaaa
	s_cmov_b32 s13, 0xaaaaaaaa
	v_cndmask_b32_e64 v252, 0, 16, s[12:13]
	v_sub_u32_e32 v201, v201, v252
	v_add_u32_e32 v154, v154, v201
	s_mov_b32 s12, 0x55555555
	s_mov_b32 s13, 0x55555555
	s_bitcmp1_b32 s15, 6
	s_cmov_b32 s12, 0x0
	s_cmov_b32 s13, 0x0
	v_cndmask_b32_e64 v201, 0, 16, s[12:13]
	s_mov_b32 s12, 0x0
	s_mov_b32 s13, 0x0
	s_bitcmp1_b32 s15, 6
	s_cmov_b32 s12, 0x55555555
	s_cmov_b32 s13, 0x55555555
	v_cndmask_b32_e64 v252, 0, 16, s[12:13]
	v_sub_u32_e32 v201, v201, v252
	v_add_u32_e32 v185, v185, v201
	s_mov_b32 s12, 0xff0000
	s_mov_b32 s13, 0xff
	v_cndmask_b32_e64 v201, 0, 16, s[12:13]
	s_mov_b32 s12, 0xff000000
	s_mov_b32 s13, 0xff00
	v_cndmask_b32_e64 v252, 0, 16, s[12:13]
	v_sub_u32_e32 v201, v201, v252
	v_add_u32_e32 v155, v155, v201
	s_mov_b32 s12, 0xff0000
	s_mov_b32 s13, 0xff
	v_cndmask_b32_e64 v201, 0, 16, s[12:13]
	s_mov_b32 s12, 0xff000000
	s_mov_b32 s13, 0xff00
	v_cndmask_b32_e64 v252, 0, 16, s[12:13]
	v_sub_u32_e32 v201, v201, v252
	v_add_u32_e32 v156, v156, v201
	v_readfirstlane_b32 s15, v202
	s_mov_b32 s12, 0xff0
	s_mov_b32 s13, 0xff0
	v_cndmask_b32_e64 v228, 0, 16, s[12:13]
	s_mov_b32 s12, 0xff00000
	s_mov_b32 s13, 0xff00000
	v_cndmask_b32_e64 v229, 0, 16, s[12:13]
	v_sub_u32_e32 v228, v228, v229
	v_add_u32_e32 v108, v108, v228
	s_mov_b32 s12, 0xff0
	s_mov_b32 s13, 0xff0
	v_cndmask_b32_e64 v228, 0, 16, s[12:13]
	s_mov_b32 s12, 0xff00000
	s_mov_b32 s13, 0xff00000
	v_cndmask_b32_e64 v229, 0, 16, s[12:13]
	v_sub_u32_e32 v228, v228, v229
	v_add_u32_e32 v109, v109, v228
	s_mov_b32 s82, s96
	s_branch .LBB0_194

; __device__ __forceinline__ unsigned f2bf(float f) { return pk2(f, 0.f) & 0xffffu; }
; template <bool PA> ...
;     ...
;         for (int i = tid; i < 4096; i += 512) { const int l = i >> 6, cc = i & 63; w2T[cc * 72 + l] = (bf16)f2bf(w2[(size_t)l * 1024 + head * 64 + cc]); a2T[cc * 72 + l] = (bf16)f2bf(a2[(size_t)l * 1024 + head * 64 + cc]); }
.LBB0_210:
	v_ashrrev_i32_e32 v4, 6, v2
	v_ashrrev_i32_e32 v5, 31, v4
	v_lshlrev_b64 v[6:7], 12, v[4:5]
	v_lshl_or_b32 v6, v0, 2, v6
	v_add_u32_e32 v4, v4, v135
	v_lshl_add_u32 v8, v4, 1, 0
	v_add_u32_e32 v222, 0x1d400, v8
	v_add_u32_e32 v223, 0x1f800, v8
	v_lshl_add_u64 v[220:221], s[20:21], 0, v[6:7]
	global_load_dword v204, v[220:221], off
	v_lshl_add_u64 v[220:221], s[76:77], 0, v[6:7]
	global_load_dword v205, v[220:221], off
	s_add_u32 s20, s20, 0x8000
	s_addc_u32 s21, s21, 0
	s_add_u32 s76, s76, 0x8000
	s_addc_u32 s77, s77, 0
	v_lshl_add_u64 v[220:221], s[20:21], 0, v[6:7]
	global_load_dword v206, v[220:221], off
	v_lshl_add_u64 v[220:221], s[76:77], 0, v[6:7]
	global_load_dword v207, v[220:221], off
	s_add_u32 s20, s20, 0x8000
	s_addc_u32 s21, s21, 0
	s_add_u32 s76, s76, 0x8000
	s_addc_u32 s77, s77, 0
	v_lshl_add_u64 v[220:221], s[20:21], 0, v[6:7]
	global_load_dword v208, v[220:221], off
	v_lshl_add_u64 v[220:221], s[76:77], 0, v[6:7]
	global_load_dword v209, v[220:221], off
	s_add_u32 s20, s20, 0x8000
	s_addc_u32 s21, s21, 0
	s_add_u32 s76, s76, 0x8000
	s_addc_u32 s77, s77, 0
	v_lshl_add_u64 v[220:221], s[20:21], 0, v[6:7]
	global_load_dword v210, v[220:221], off
	v_lshl_add_u64 v[220:221], s[76:77], 0, v[6:7]
	global_load_dword v211, v[220:221], off
	s_add_u32 s20, s20, 0x8000
	s_addc_u32 s21, s21, 0
	s_add_u32 s76, s76, 0x8000
	s_addc_u32 s77, s77, 0
	v_lshl_add_u64 v[220:221], s[20:21], 0, v[6:7]
	global_load_dword v212, v[220:221], off
	v_lshl_add_u64 v[220:221], s[76:77], 0, v[6:7]
	global_load_dword v213, v[220:221], off
	s_add_u32 s20, s20, 0x8000
	s_addc_u32 s21, s21, 0
	s_add_u32 s76, s76, 0x8000
	s_addc_u32 s77, s77, 0
	v_lshl_add_u64 v[220:221], s[20:21], 0, v[6:7]
	global_load_dword v214, v[220:221], off
	v_lshl_add_u64 v[220:221], s[76:77], 0, v[6:7]
	global_load_dword v215, v[220:221], off
	s_add_u32 s20, s20, 0x8000
	s_addc_u32 s21, s21, 0
	s_add_u32 s76, s76, 0x8000
	s_addc_u32 s77, s77, 0
	v_lshl_add_u64 v[220:221], s[20:21], 0, v[6:7]
	global_load_dword v216, v[220:221], off
	v_lshl_add_u64 v[220:221], s[76:77], 0, v[6:7]
	global_load_dword v217, v[220:221], off
	s_add_u32 s20, s20, 0x8000
	s_addc_u32 s21, s21, 0
	s_add_u32 s76, s76, 0x8000
	s_addc_u32 s77, s77, 0
	v_lshl_add_u64 v[220:221], s[20:21], 0, v[6:7]
	global_load_dword v218, v[220:221], off
	v_lshl_add_u64 v[220:221], s[76:77], 0, v[6:7]
	global_load_dword v219, v[220:221], off
	s_sub_u32 s20, s20, 0x38000
	s_subb_u32 s21, s21, 0
	s_sub_u32 s76, s76, 0x38000
	s_subb_u32 s77, s77, 0
	s_waitcnt vmcnt(15)
	v_cvt_pk_bf16_f32 v3, v204, s0
	v_and_b32_e32 v228, 15, v203
	v_add_u32_e32 v228, 4, v228
	v_and_b32_e32 v228, 8, v228
	v_lshlrev_b32_e32 v228, 1, v228
	v_add_u32_e32 v194, v222, v228
	v_sub_u32_e32 v195, v222, v228
	v_add_u32_e32 v200, v223, v228
	v_sub_u32_e32 v228, v223, v228
	ds_write_b16 v194, v3 offset:0
	s_waitcnt vmcnt(14)
	v_cvt_pk_bf16_f32 v9, v205, s0
	ds_write_b16 v200, v9 offset:0
	s_waitcnt vmcnt(13)
	v_cvt_pk_bf16_f32 v3, v206, s0
	ds_write_b16 v195, v3 offset:16
	s_waitcnt vmcnt(12)
	v_cvt_pk_bf16_f32 v9, v207, s0
	ds_write_b16 v228, v9 offset:16
	s_waitcnt vmcnt(11)
	v_cvt_pk_bf16_f32 v3, v208, s0
	ds_write_b16 v194, v3 offset:32
	s_waitcnt vmcnt(10)
	v_cvt_pk_bf16_f32 v9, v209, s0
	ds_write_b16 v200, v9 offset:32
	s_waitcnt vmcnt(9)
	v_cvt_pk_bf16_f32 v3, v210, s0
	ds_write_b16 v195, v3 offset:48
	s_waitcnt vmcnt(8)
	v_cvt_pk_bf16_f32 v9, v211, s0
	ds_write_b16 v228, v9 offset:48
	s_waitcnt vmcnt(7)
	v_cvt_pk_bf16_f32 v3, v212, s0
	ds_write_b16 v194, v3 offset:64
	s_waitcnt vmcnt(6)
	v_cvt_pk_bf16_f32 v9, v213, s0
	ds_write_b16 v200, v9 offset:64
	s_waitcnt vmcnt(5)
	v_cvt_pk_bf16_f32 v3, v214, s0
	ds_write_b16 v195, v3 offset:80
	s_waitcnt vmcnt(4)
	v_cvt_pk_bf16_f32 v9, v215, s0
	ds_write_b16 v228, v9 offset:80
	s_waitcnt vmcnt(3)
	v_cvt_pk_bf16_f32 v3, v216, s0
	ds_write_b16 v194, v3 offset:96
	s_waitcnt vmcnt(2)
	v_cvt_pk_bf16_f32 v9, v217, s0
	ds_write_b16 v200, v9 offset:96
	s_waitcnt vmcnt(1)
	v_cvt_pk_bf16_f32 v3, v218, s0
	ds_write_b16 v195, v3 offset:112
	s_waitcnt vmcnt(0)
	v_cvt_pk_bf16_f32 v9, v219, s0
	ds_write_b16 v228, v9 offset:112
